# grid barrier: non-last workgroups of an XCD wait on the cross-XCD release generation directly instead of the per-XCD word bumped afterwards (one atomic+poll hop less)
# speedup vs baseline: 1.0087x; 1.0014x over previous
.LBB0_146:
	s_or_b64 exec, exec, s[10:11]
	v_cvt_f32_u32_e32 v4, v2
	s_waitcnt vmcnt(0)
	v_readfirstlane_b32 s8, v3
	v_sub_u32_e32 v3, 0, v2
	v_rcp_iflag_f32_e32 v4, v4
	v_add_u32_e32 v5, s8, v1
	v_mul_f32_e32 v4, 0x4f7ffffe, v4
	v_cvt_u32_f32_e32 v4, v4
	v_mul_lo_u32 v1, v3, v4
	v_mul_hi_u32 v1, v4, v1
	v_add_u32_e32 v1, v4, v1
	v_mul_hi_u32 v1, v5, v1
	v_mul_lo_u32 v3, v1, v2
	v_sub_u32_e32 v3, v5, v3
	v_add_u32_e32 v4, 1, v1
	v_cmp_ge_u32_e32 vcc, v3, v2
	s_nop 1
	v_cndmask_b32_e32 v1, v1, v4, vcc
	v_sub_u32_e32 v4, v3, v2
	v_cndmask_b32_e32 v3, v3, v4, vcc
	v_add_u32_e32 v4, 1, v1
	v_cmp_ge_u32_e32 vcc, v3, v2
	v_add_u32_e32 v3, 1, v5
	s_nop 0
	v_cndmask_b32_e32 v1, v1, v4, vcc
	v_mul_lo_u32 v4, v2, v1
	v_add_u32_e32 v2, v4, v2
	v_cmp_ne_u32_e32 vcc, v3, v2
	s_and_saveexec_b64 s[8:9], vcc
	s_xor_b64 s[8:9], exec, s[8:9]
	s_cbranch_execz .LBB0_160
	s_waitcnt lgkmcnt(0)
	v_mov_b32_e32 v0, 0x7100
	global_load_dword v0, v0, s[4:5] offset:1024 sc1
	s_add_u32 s16, s4, 0x7500
	s_addc_u32 s17, s5, 0
	s_waitcnt vmcnt(0)
	v_cmp_eq_u32_e32 vcc, v0, v1
	s_and_saveexec_b64 s[10:11], vcc
	s_cbranch_execz .LBB0_159
	s_add_u32 s12, s4, 0x4200
	s_addc_u32 s13, s5, 0
	s_mov_b32 s18, 1
	s_mov_b64 s[20:21], 0
	v_mov_b32_e32 v0, 0
	s_branch .LBB0_150

.LBB0_269:
	s_or_b64 exec, exec, s[14:15]
	v_cvt_f32_u32_e32 v4, v2
	s_waitcnt vmcnt(0)
	v_readfirstlane_b32 s12, v3
	v_sub_u32_e32 v3, 0, v2
	v_rcp_iflag_f32_e32 v4, v4
	v_add_u32_e32 v5, s12, v1
	v_mul_f32_e32 v4, 0x4f7ffffe, v4
	v_cvt_u32_f32_e32 v4, v4
	v_mul_lo_u32 v1, v3, v4
	v_mul_hi_u32 v1, v4, v1
	v_add_u32_e32 v1, v4, v1
	v_mul_hi_u32 v1, v5, v1
	v_mul_lo_u32 v3, v1, v2
	v_sub_u32_e32 v3, v5, v3
	v_add_u32_e32 v4, 1, v1
	v_cmp_ge_u32_e32 vcc, v3, v2
	s_nop 1
	v_cndmask_b32_e32 v1, v1, v4, vcc
	v_sub_u32_e32 v4, v3, v2
	v_cndmask_b32_e32 v3, v3, v4, vcc
	v_add_u32_e32 v4, 1, v1
	v_cmp_ge_u32_e32 vcc, v3, v2
	v_add_u32_e32 v3, 1, v5
	s_nop 0
	v_cndmask_b32_e32 v1, v1, v4, vcc
	v_mul_lo_u32 v4, v2, v1
	v_add_u32_e32 v2, v4, v2
	v_cmp_ne_u32_e32 vcc, v3, v2
	s_and_saveexec_b64 s[12:13], vcc
	s_xor_b64 s[12:13], exec, s[12:13]
	s_cbranch_execz .LBB0_283
	s_waitcnt lgkmcnt(0)
	v_mov_b32_e32 v0, 0x7100
	global_load_dword v0, v0, s[6:7] offset:1024 sc1
	s_add_u32 s22, s6, 0x7500
	s_addc_u32 s23, s7, 0
	s_waitcnt vmcnt(0)
	v_cmp_eq_u32_e32 vcc, v0, v1
	s_and_saveexec_b64 s[16:17], vcc
	s_cbranch_execz .LBB0_282
	s_add_u32 s20, s6, 0x4200
	s_addc_u32 s21, s7, 0
	s_mov_b32 s34, 1
	s_mov_b64 s[24:25], 0
	s_branch .LBB0_273

.LBB0_520:
	s_or_b64 exec, exec, s[12:13]
	v_cvt_f32_u32_e32 v4, v2
	s_waitcnt vmcnt(0)
	v_readfirstlane_b32 s10, v3
	v_sub_u32_e32 v3, 0, v2
	v_rcp_iflag_f32_e32 v4, v4
	v_add_u32_e32 v5, s10, v1
	v_mul_f32_e32 v4, 0x4f7ffffe, v4
	v_cvt_u32_f32_e32 v4, v4
	v_mul_lo_u32 v1, v3, v4
	v_mul_hi_u32 v1, v4, v1
	v_add_u32_e32 v1, v4, v1
	v_mul_hi_u32 v1, v5, v1
	v_mul_lo_u32 v3, v1, v2
	v_sub_u32_e32 v3, v5, v3
	v_add_u32_e32 v4, 1, v1
	v_cmp_ge_u32_e32 vcc, v3, v2
	s_nop 1
	v_cndmask_b32_e32 v1, v1, v4, vcc
	v_sub_u32_e32 v4, v3, v2
	v_cndmask_b32_e32 v3, v3, v4, vcc
	v_add_u32_e32 v4, 1, v1
	v_cmp_ge_u32_e32 vcc, v3, v2
	v_add_u32_e32 v3, 1, v5
	s_nop 0
	v_cndmask_b32_e32 v1, v1, v4, vcc
	v_mul_lo_u32 v4, v2, v1
	v_add_u32_e32 v2, v4, v2
	v_cmp_ne_u32_e32 vcc, v3, v2
	s_and_saveexec_b64 s[10:11], vcc
	s_xor_b64 s[10:11], exec, s[10:11]
	s_cbranch_execz .LBB0_534
	s_waitcnt lgkmcnt(0)
	v_mov_b32_e32 v0, 0x7100
	global_load_dword v0, v0, s[6:7] offset:1024 sc1
	s_add_u32 s20, s6, 0x7500
	s_addc_u32 s21, s7, 0
	s_waitcnt vmcnt(0)
	v_cmp_eq_u32_e32 vcc, v0, v1
	s_and_saveexec_b64 s[12:13], vcc
	s_cbranch_execz .LBB0_533
	s_add_u32 s16, s6, 0x4200
	s_addc_u32 s17, s7, 0
	s_mov_b32 s30, 1
	s_mov_b64 s[22:23], 0
	s_branch .LBB0_524

.LBB0_682:
	s_or_b64 exec, exec, s[10:11]
	v_cvt_f32_u32_e32 v4, v2
	s_waitcnt vmcnt(0)
	v_readfirstlane_b32 s8, v3
	v_sub_u32_e32 v3, 0, v2
	v_rcp_iflag_f32_e32 v4, v4
	v_add_u32_e32 v5, s8, v1
	v_mul_f32_e32 v4, 0x4f7ffffe, v4
	v_cvt_u32_f32_e32 v4, v4
	v_mul_lo_u32 v1, v3, v4
	v_mul_hi_u32 v1, v4, v1
	v_add_u32_e32 v1, v4, v1
	v_mul_hi_u32 v1, v5, v1
	v_mul_lo_u32 v3, v1, v2
	v_sub_u32_e32 v3, v5, v3
	v_add_u32_e32 v4, 1, v1
	v_cmp_ge_u32_e32 vcc, v3, v2
	s_nop 1
	v_cndmask_b32_e32 v1, v1, v4, vcc
	v_sub_u32_e32 v4, v3, v2
	v_cndmask_b32_e32 v3, v3, v4, vcc
	v_add_u32_e32 v4, 1, v1
	v_cmp_ge_u32_e32 vcc, v3, v2
	v_add_u32_e32 v3, 1, v5
	s_nop 0
	v_cndmask_b32_e32 v1, v1, v4, vcc
	v_mul_lo_u32 v4, v2, v1
	v_add_u32_e32 v2, v4, v2
	v_cmp_ne_u32_e32 vcc, v3, v2
	s_and_saveexec_b64 s[8:9], vcc
	s_xor_b64 s[8:9], exec, s[8:9]
	s_cbranch_execz .LBB0_696
	s_waitcnt lgkmcnt(0)
	v_mov_b32_e32 v0, 0x7100
	global_load_dword v0, v0, s[4:5] offset:1024 sc1
	s_add_u32 s16, s4, 0x7500
	s_addc_u32 s17, s5, 0
	s_waitcnt vmcnt(0)
	v_cmp_eq_u32_e32 vcc, v0, v1
	s_and_saveexec_b64 s[10:11], vcc
	s_cbranch_execz .LBB0_695
	s_add_u32 s12, s4, 0x4200
	s_addc_u32 s13, s5, 0
	s_mov_b32 s28, 1
	s_mov_b64 s[20:21], 0
	s_branch .LBB0_686

.LBB0_989:
	s_or_b64 exec, exec, s[14:15]
	v_cvt_f32_u32_e32 v4, v2
	s_waitcnt vmcnt(0)
	v_readfirstlane_b32 s8, v3
	v_sub_u32_e32 v3, 0, v2
	v_rcp_iflag_f32_e32 v4, v4
	v_add_u32_e32 v5, s8, v1
	v_mul_f32_e32 v4, 0x4f7ffffe, v4
	v_cvt_u32_f32_e32 v4, v4
	v_mul_lo_u32 v1, v3, v4
	v_mul_hi_u32 v1, v4, v1
	v_add_u32_e32 v1, v4, v1
	v_mul_hi_u32 v1, v5, v1
	v_mul_lo_u32 v3, v1, v2
	v_sub_u32_e32 v3, v5, v3
	v_add_u32_e32 v4, 1, v1
	v_cmp_ge_u32_e32 vcc, v3, v2
	s_nop 1
	v_cndmask_b32_e32 v1, v1, v4, vcc
	v_sub_u32_e32 v4, v3, v2
	v_cndmask_b32_e32 v3, v3, v4, vcc
	v_add_u32_e32 v4, 1, v1
	v_cmp_ge_u32_e32 vcc, v3, v2
	v_add_u32_e32 v3, 1, v5
	s_nop 0
	v_cndmask_b32_e32 v1, v1, v4, vcc
	v_mul_lo_u32 v4, v2, v1
	v_add_u32_e32 v2, v4, v2
	v_cmp_ne_u32_e32 vcc, v3, v2
	s_and_saveexec_b64 s[8:9], vcc
	s_xor_b64 s[22:23], exec, s[8:9]
	s_cbranch_execz .LBB0_1003
	s_waitcnt lgkmcnt(0)
	v_mov_b32_e32 v0, 0x7100
	global_load_dword v0, v0, s[4:5] offset:1024 sc1
	s_add_u32 s28, s4, 0x7500
	s_addc_u32 s29, s5, 0
	s_waitcnt vmcnt(0)
	v_cmp_eq_u32_e32 vcc, v0, v1
	s_and_saveexec_b64 s[24:25], vcc
	s_cbranch_execz .LBB0_1002
	s_add_u32 s26, s4, 0x4200
	s_addc_u32 s27, s5, 0
	s_mov_b32 s35, 1
	s_mov_b64 s[30:31], 0
	s_branch .LBB0_993

.LBB0_1086:
	s_or_b64 exec, exec, s[14:15]
	v_cvt_f32_u32_e32 v4, v2
	s_waitcnt vmcnt(0)
	v_readfirstlane_b32 s8, v3
	v_sub_u32_e32 v3, 0, v2
	v_rcp_iflag_f32_e32 v4, v4
	v_add_u32_e32 v5, s8, v1
	v_mul_f32_e32 v4, 0x4f7ffffe, v4
	v_cvt_u32_f32_e32 v4, v4
	v_mul_lo_u32 v1, v3, v4
	v_mul_hi_u32 v1, v4, v1
	v_add_u32_e32 v1, v4, v1
	v_mul_hi_u32 v1, v5, v1
	v_mul_lo_u32 v3, v1, v2
	v_sub_u32_e32 v3, v5, v3
	v_add_u32_e32 v4, 1, v1
	v_cmp_ge_u32_e32 vcc, v3, v2
	s_nop 1
	v_cndmask_b32_e32 v1, v1, v4, vcc
	v_sub_u32_e32 v4, v3, v2
	v_cndmask_b32_e32 v3, v3, v4, vcc
	v_add_u32_e32 v4, 1, v1
	v_cmp_ge_u32_e32 vcc, v3, v2
	v_add_u32_e32 v3, 1, v5
	s_nop 0
	v_cndmask_b32_e32 v1, v1, v4, vcc
	v_mul_lo_u32 v4, v2, v1
	v_add_u32_e32 v2, v4, v2
	v_cmp_ne_u32_e32 vcc, v3, v2
	s_and_saveexec_b64 s[8:9], vcc
	s_xor_b64 s[22:23], exec, s[8:9]
	s_cbranch_execz .LBB0_1100
	s_waitcnt lgkmcnt(0)
	v_mov_b32_e32 v0, 0x7100
	global_load_dword v0, v0, s[4:5] offset:1024 sc1
	s_add_u32 s28, s4, 0x7500
	s_addc_u32 s29, s5, 0
	s_waitcnt vmcnt(0)
	v_cmp_eq_u32_e32 vcc, v0, v1
	s_and_saveexec_b64 s[24:25], vcc
	s_cbranch_execz .LBB0_1099
	s_add_u32 s26, s4, 0x4200
	s_addc_u32 s27, s5, 0
	s_mov_b32 s35, 1
	s_mov_b64 s[36:37], 0
	s_branch .LBB0_1090
